# stack: scan remap, convert load hoists, batched loads in x-conv/rstd table/mem staging, grid barrier polls cross-XCD generation directly
# baseline (speedup 1.0000x reference)
; __device__ __forceinline__ unsigned xb_ld(unsigned* p)              { return __hip_atomic_load(p, __ATOMIC_RELAXED, __HIP_MEMORY_SCOPE_AGENT); }
; __device__ __forceinline__ unsigned xb_add(unsigned* p, unsigned v) { return __hip_atomic_fetch_add(p, v, __ATOMIC_RELAXED, __HIP_MEMORY_SCOPE_AGENT); }
; #define XB_SPIN(cond, bar) do { unsigned _sp = 0; while (cond) { __builtin_amdgcn_s_sleep(1); \
;     if ((++_sp & 255u) == 0u) { if (xb_ld(&(bar)[XB_TMO])) break; if (_sp > XB_SPIN_CAP) { atomicAdd(&(bar)[XB_TMO], 1u); break; } } } } while (0)
; __device__ __forceinline__ void xcd_barrier(const XcdBarrier& b) {
;     ...
;         const unsigned old = xb_add(&bar[XB_XSUB(b.x)], 1u);
;         const unsigned gen = old / nloc;
;         if (old + 1u == (gen + 1u) * nloc) {
;             __builtin_amdgcn_fence(__ATOMIC_RELEASE, "agent");
;             asm volatile("s_waitcnt vmcnt(0)" ::: "memory");
;             const unsigned og = xb_add(&bar[XB_TOP], 1u);
;             const unsigned tg = og / nx;
;             if (og + 1u == (tg + 1u) * nx) xb_add(&bar[XB_TOPGEN], 1u);
;             else XB_SPIN(xb_ld(&bar[XB_TOPGEN]) == tg, bar);
;             __builtin_amdgcn_fence(__ATOMIC_ACQUIRE, "agent");
;             xb_add(&bar[XB_XGEN(b.x)], 1u);
;             asm volatile("s_waitcnt vmcnt(0)" ::: "memory");
;         } else {
;             XB_SPIN(xb_ld(&bar[XB_XGEN(b.x)]) == gen, bar);
.LBB0_76:
	s_or_b64 exec, exec, s[8:9]
	v_cvt_f32_u32_e32 v5, v3
	s_waitcnt vmcnt(0)
	v_readfirstlane_b32 s6, v4
	v_sub_u32_e32 v4, 0, v3
	v_rcp_iflag_f32_e32 v5, v5
	v_add_u32_e32 v6, s6, v2
	v_mul_f32_e32 v5, 0x4f7ffffe, v5
	v_cvt_u32_f32_e32 v5, v5
	v_mul_lo_u32 v2, v4, v5
	v_mul_hi_u32 v2, v5, v2
	v_add_u32_e32 v2, v5, v2
	v_mul_hi_u32 v2, v6, v2
	v_mul_lo_u32 v4, v2, v3
	v_sub_u32_e32 v4, v6, v4
	v_add_u32_e32 v5, 1, v2
	v_cmp_ge_u32_e32 vcc, v4, v3
	s_nop 1
	v_cndmask_b32_e32 v2, v2, v5, vcc
	v_sub_u32_e32 v5, v4, v3
	v_cndmask_b32_e32 v4, v4, v5, vcc
	v_add_u32_e32 v5, 1, v2
	v_cmp_ge_u32_e32 vcc, v4, v3
	v_add_u32_e32 v4, 1, v6
	s_nop 0
	v_cndmask_b32_e32 v2, v2, v5, vcc
	v_mul_lo_u32 v5, v3, v2
	v_add_u32_e32 v3, v5, v3
	v_cmp_ne_u32_e32 vcc, v4, v3
	s_and_saveexec_b64 s[6:7], vcc
	s_xor_b64 s[6:7], exec, s[6:7]
	s_cbranch_execz .LBB0_90
	s_waitcnt lgkmcnt(0)
	v_mov_b32_e32 v1, 0x3100
	global_load_dword v1, v1, s[78:79] offset:1024 sc1
	s_add_u32 s10, s78, 0x3500
	s_addc_u32 s11, s79, 0
	s_waitcnt vmcnt(0)
	v_cmp_eq_u32_e32 vcc, v1, v2
	s_and_saveexec_b64 s[8:9], vcc
	s_cbranch_execz .LBB0_89
	s_mov_b32 s22, 1
	s_mov_b64 s[12:13], 0
	v_mov_b32_e32 v1, 0
	s_branch .LBB0_80

; __device__ __forceinline__ unsigned xb_add(unsigned* p, unsigned v) { return __hip_atomic_fetch_add(p, v, __ATOMIC_RELAXED, __HIP_MEMORY_SCOPE_AGENT); }
; __device__ __forceinline__ void xcd_barrier(const XcdBarrier& b) {
;     ...
;             __builtin_amdgcn_fence(__ATOMIC_ACQUIRE, "agent");
;             xb_add(&bar[XB_XGEN(b.x)], 1u);
;             asm volatile("s_waitcnt vmcnt(0)" ::: "memory");
.LBB0_107:
	s_or_b64 exec, exec, s[6:7]
	s_mov_b64 s[6:7], exec
	v_mbcnt_lo_u32_b32 v1, s6, 0
	v_mbcnt_hi_u32_b32 v1, s7, v1
	v_cmp_eq_u32_e32 vcc, 0, v1
	s_waitcnt vmcnt(0)
	buffer_inv sc1
	s_and_saveexec_b64 s[8:9], vcc
	s_cbranch_execz .LBB0_109
	s_bcnt1_i32_b64 s6, s[6:7]
	v_mov_b32_e32 v1, 0x2000
	v_mov_b32_e32 v2, s6
	s_nop 0

; #define LAS __attribute__((address_space(3)))
; __device__ __forceinline__ void mem_unit(Frame& F, const int layer, const int ldp, const int xq_off, const int unit) {
;     ...
; #pragma unroll
;     for (int q = 0; q < 8; ++q) { const int p = F.tid + 512 * q, key = p >> 4, c = p & 15;
;         *(LAS v4u*)(Ks + key * KP + c * 16) = *(const v4u*)(MKV + (size_t)(b * MEMLEN + key) * 4096 + layer * 1024 + head * 128 + 8 * c); }
; #pragma unroll
;     for (int q = 0; q < 8; ++q) { const int p = F.tid + 512 * q, key = p & 255, c = p >> 8;
;         const v4u val = *(const v4u*)(MKV + (size_t)(b * MEMLEN + key) * 4096 + layer * 1024 + 512 + head * 128 + 8 * c);
;         const ldsp vb = Vt + (8 * c) * VP + key * 2;
;         *(LAS bf16*)(vb) = (bf16)(val.x & 0xffff); *(LAS bf16*)(vb + VP) = (bf16)(val.x >> 16); *(LAS bf16*)(vb + 2 * VP) = (bf16)(val.y & 0xffff); *(LAS bf16*)(vb + 3 * VP) = (bf16)(val.y >> 16);
;         *(LAS bf16*)(vb + 4 * VP) = (bf16)(val.z & 0xffff); *(LAS bf16*)(vb + 5 * VP) = (bf16)(val.z >> 16); *(LAS bf16*)(vb + 6 * VP) = (bf16)(val.w & 0xffff); *(LAS bf16*)(vb + 7 * VP) = (bf16)(val.w >> 16); }
;     __syncthreads();
;     const int r = F.lane & 31, h = F.lane >> 5;
;     const size_t row = (size_t)b * SEQ + tb * 256 + 32 * F.wave + r;
;     bf16x8 qf[8];
; #pragma unroll
;     for (int ks = 0; ks < 8; ++ks) qf[ks] = *(const bf16x8*)(P + row * ldp + xq_off + head * 128 + 16 * ks + 8 * h);
;     f32x16 o[4];
; #pragma unroll
;     for (int dt = 0; dt < 4; ++dt)
; #pragma unroll
;         for (int i = 0; i < 16; ++i) o[dt][i] = 0.f;
;     float m = -1e30f, l = 0.f; const NoMask nm;
.LBB0_365:
	s_ashr_i32 s4, s8, 6
	s_lshl_b32 s9, s8, 3
	s_lshl_b32 s5, s4, 8
	s_and_b32 s9, s9, 0x180
	s_lshl_b32 s26, s9, 1
	v_add_u32_e32 v0, s5, v156
	s_add_u32 s14, s0, s26
	v_ashrrev_i32_e32 v1, 31, v0
	s_addc_u32 s15, s1, 0
	v_lshlrev_b64 v[0:1], 13, v[0:1]
	v_lshl_add_u64 v[0:1], s[14:15], 0, v[0:1]
	v_mov_b32_e32 v149, v96
	v_lshl_add_u64 v[0:1], v[0:1], 0, v[148:149]
	flat_load_dwordx4 v[208:211], v[0:1]
	s_lshl_b32 s10, s8, 8
	s_and_b32 s10, s10, 0xf00
	v_mov_b32_e32 v151, v96
	v_mov_b32_e32 v72, 0
	v_mov_b32_e32 v183, 0xf149f2ca
	v_mov_b32_e32 v48, 0
	v_mov_b32_e32 v49, v72
	v_mov_b32_e32 v50, v72
	v_mov_b32_e32 v51, v72
	v_mov_b32_e32 v52, v72
	v_mov_b32_e32 v53, v72
	v_mov_b32_e32 v54, v72
	v_mov_b32_e32 v55, v72
	v_mov_b32_e32 v56, v72
	v_mov_b32_e32 v57, v72
	v_mov_b32_e32 v58, v72
	v_mov_b32_e32 v59, v72
	v_mov_b32_e32 v60, v72
	v_mov_b32_e32 v61, v72
	v_mov_b32_e32 v62, v72
	v_mov_b32_e32 v63, v72
	v_mov_b32_e32 v32, 0
	v_mov_b32_e32 v33, v72
	v_mov_b32_e32 v34, v72
	v_mov_b32_e32 v35, v72
	v_mov_b32_e32 v36, v72
	v_mov_b32_e32 v37, v72
	v_mov_b32_e32 v38, v72
	v_mov_b32_e32 v39, v72
	v_mov_b32_e32 v40, v72
	v_mov_b32_e32 v41, v72
	v_mov_b32_e32 v42, v72
	v_mov_b32_e32 v43, v72
	v_mov_b32_e32 v44, v72
	v_mov_b32_e32 v45, v72
	v_mov_b32_e32 v46, v72
	v_mov_b32_e32 v47, v72
	v_mov_b32_e32 v16, 0
	v_mov_b32_e32 v17, v72
	v_mov_b32_e32 v18, v72
	v_mov_b32_e32 v19, v72
	v_mov_b32_e32 v20, v72
	v_mov_b32_e32 v21, v72
	v_mov_b32_e32 v22, v72
	v_mov_b32_e32 v23, v72
	v_mov_b32_e32 v24, v72
	v_mov_b32_e32 v25, v72
	v_mov_b32_e32 v26, v72
	v_mov_b32_e32 v27, v72
	v_mov_b32_e32 v28, v72
	v_mov_b32_e32 v29, v72
	v_mov_b32_e32 v30, v72
	v_mov_b32_e32 v31, v72
	v_mov_b32_e32 v6, v72
	v_mov_b32_e32 v7, v72
	v_mov_b32_e32 v8, v72
	v_mov_b32_e32 v9, v72
	v_mov_b32_e32 v10, v72
	v_mov_b32_e32 v11, v72
	v_mov_b32_e32 v12, v72
	v_mov_b32_e32 v13, v72
	v_mov_b32_e32 v14, v72
	v_mov_b32_e32 v15, v72
	v_add_u32_e32 v0, s5, v157
	v_ashrrev_i32_e32 v1, 31, v0
	v_lshlrev_b64 v[0:1], 13, v[0:1]
	v_lshl_add_u64 v[0:1], s[14:15], 0, v[0:1]
	v_lshl_add_u64 v[0:1], v[0:1], 0, v[148:149]
	flat_load_dwordx4 v[212:215], v[0:1]
	v_add_u32_e32 v0, s5, v158
	v_ashrrev_i32_e32 v1, 31, v0
	v_lshlrev_b64 v[0:1], 13, v[0:1]
	v_lshl_add_u64 v[0:1], s[14:15], 0, v[0:1]
	v_lshl_add_u64 v[0:1], v[0:1], 0, v[148:149]
	flat_load_dwordx4 v[216:219], v[0:1]
	v_add_u32_e32 v0, s5, v159
	v_ashrrev_i32_e32 v1, 31, v0
	v_lshlrev_b64 v[0:1], 13, v[0:1]
	v_lshl_add_u64 v[0:1], s[14:15], 0, v[0:1]
	v_lshl_add_u64 v[0:1], v[0:1], 0, v[148:149]
	flat_load_dwordx4 v[220:223], v[0:1]
	v_add_u32_e32 v0, s5, v160
	v_ashrrev_i32_e32 v1, 31, v0
	v_lshlrev_b64 v[0:1], 13, v[0:1]
	v_lshl_add_u64 v[0:1], s[14:15], 0, v[0:1]
	v_lshl_add_u64 v[0:1], v[0:1], 0, v[148:149]
	flat_load_dwordx4 v[224:227], v[0:1]
	v_add_u32_e32 v0, s5, v161
	v_ashrrev_i32_e32 v1, 31, v0
	v_lshlrev_b64 v[0:1], 13, v[0:1]
	v_lshl_add_u64 v[0:1], s[14:15], 0, v[0:1]
	v_lshl_add_u64 v[0:1], v[0:1], 0, v[148:149]
	flat_load_dwordx4 v[228:231], v[0:1]
	v_add_u32_e32 v0, s5, v162
	v_ashrrev_i32_e32 v1, 31, v0
	v_lshlrev_b64 v[0:1], 13, v[0:1]
	v_lshl_add_u64 v[0:1], s[14:15], 0, v[0:1]
	v_lshl_add_u64 v[0:1], v[0:1], 0, v[148:149]
	flat_load_dwordx4 v[232:235], v[0:1]
	v_add_u32_e32 v0, s5, v163
	v_ashrrev_i32_e32 v1, 31, v0
	v_lshlrev_b64 v[0:1], 13, v[0:1]
	v_lshl_add_u64 v[0:1], s[14:15], 0, v[0:1]
	v_lshl_add_u64 v[0:1], v[0:1], 0, v[148:149]
	s_waitcnt vmcnt(0) lgkmcnt(0)
	ds_write_b128 v167, v[208:211]
	ds_write_b128 v168, v[212:215]
	ds_write_b128 v169, v[216:219]
	ds_write_b128 v170, v[220:223]
	ds_write_b128 v171, v[224:227]
	ds_write_b128 v172, v[228:231]
	ds_write_b128 v173, v[232:235]
	flat_load_dwordx4 v[208:211], v[0:1]
	v_mov_b32_e32 v149, v166
	v_or_b32_e32 v0, s5, v164
	v_ashrrev_i32_e32 v1, 31, v0
	v_lshlrev_b64 v[0:1], 13, v[0:1]
	v_lshl_add_u64 v[0:1], s[0:1], 0, v[0:1]
	v_lshl_add_u64 v[0:1], v[0:1], 0, s[26:27]
	v_lshl_add_u64 v[2:3], v[130:131], 1, v[0:1]
	flat_load_dwordx4 v[212:215], v[2:3] offset:1024
	s_ashr_i32 s5, s4, 31
	s_lshl_b64 s[4:5], s[4:5], 12
	s_or_b32 s4, s4, s10
	v_lshl_add_u64 v[154:155], s[4:5], 0, v[146:147]
	v_lshl_add_u64 v[2:3], v[132:133], 1, v[0:1]
	flat_load_dwordx4 v[216:219], v[2:3] offset:1024
	v_lshl_add_u64 v[2:3], v[134:135], 1, v[0:1]
	flat_load_dwordx4 v[220:223], v[2:3] offset:1024
	v_lshl_add_u64 v[2:3], v[136:137], 1, v[0:1]
	flat_load_dwordx4 v[224:227], v[2:3] offset:1024
	v_lshl_add_u64 v[2:3], v[138:139], 1, v[0:1]
	flat_load_dwordx4 v[228:231], v[2:3] offset:1024
	v_lshl_add_u64 v[2:3], v[140:141], 1, v[0:1]
	flat_load_dwordx4 v[232:235], v[2:3] offset:1024
	v_lshl_add_u64 v[2:3], v[142:143], 1, v[0:1]
	s_waitcnt vmcnt(0) lgkmcnt(0)
; #define LAS __attribute__((address_space(3)))
; __device__ __forceinline__ void mem_unit(Frame& F, const int layer, const int ldp, const int xq_off, const int unit) {
;     ...
;     for (int q = 0; q < 8; ++q) { const int p = F.tid + 512 * q, key = p & 255, c = p >> 8;
;         const v4u val = *(const v4u*)(MKV + (size_t)(b * MEMLEN + key) * 4096 + layer * 1024 + 512 + head * 128 + 8 * c);
;         const ldsp vb = Vt + (8 * c) * VP + key * 2;
;         *(LAS bf16*)(vb) = (bf16)(val.x & 0xffff); *(LAS bf16*)(vb + VP) = (bf16)(val.x >> 16); *(LAS bf16*)(vb + 2 * VP) = (bf16)(val.y & 0xffff); *(LAS bf16*)(vb + 3 * VP) = (bf16)(val.y >> 16);
;         *(LAS bf16*)(vb + 4 * VP) = (bf16)(val.z & 0xffff); *(LAS bf16*)(vb + 5 * VP) = (bf16)(val.z >> 16); *(LAS bf16*)(vb + 6 * VP) = (bf16)(val.w & 0xffff); *(LAS bf16*)(vb + 7 * VP) = (bf16)(val.w >> 16); }
;     __syncthreads();
;     const int r = F.lane & 31, h = F.lane >> 5;
;     const size_t row = (size_t)b * SEQ + tb * 256 + 32 * F.wave + r;
;     bf16x8 qf[8];
; #pragma unroll
;     for (int ks = 0; ks < 8; ++ks) qf[ks] = *(const bf16x8*)(P + row * ldp + xq_off + head * 128 + 16 * ks + 8 * h);
	ds_write_b128 v174, v[208:211]
	ds_write_b16 v175, v212
	ds_write_b16_d16_hi v175, v212 offset:520
	ds_write_b16 v175, v213 offset:1040
	ds_write_b16_d16_hi v175, v213 offset:1560
	ds_write_b16 v175, v214 offset:2080
	ds_write_b16_d16_hi v175, v214 offset:2600
	ds_write_b16 v175, v215 offset:3120
	ds_write_b16_d16_hi v175, v215 offset:3640
	ds_write_b16 v176, v216
	ds_write_b16_d16_hi v176, v216 offset:520
	ds_write_b16 v176, v217 offset:1040
	ds_write_b16_d16_hi v176, v217 offset:1560
	ds_write_b16 v176, v218 offset:2080
	ds_write_b16_d16_hi v176, v218 offset:2600
	ds_write_b16 v176, v219 offset:3120
	ds_write_b16_d16_hi v176, v219 offset:3640
	ds_write_b16 v177, v220
	ds_write_b16_d16_hi v177, v220 offset:520
	ds_write_b16 v177, v221 offset:1040
	ds_write_b16_d16_hi v177, v221 offset:1560
	ds_write_b16 v177, v222 offset:2080
	ds_write_b16_d16_hi v177, v222 offset:2600
	ds_write_b16 v177, v223 offset:3120
	ds_write_b16_d16_hi v177, v223 offset:3640
	ds_write_b16 v178, v224
	ds_write_b16_d16_hi v178, v224 offset:520
	ds_write_b16 v178, v225 offset:1040
	ds_write_b16_d16_hi v178, v225 offset:1560
	ds_write_b16 v178, v226 offset:2080
	ds_write_b16_d16_hi v178, v226 offset:2600
	ds_write_b16 v178, v227 offset:3120
	ds_write_b16_d16_hi v178, v227 offset:3640
	ds_write_b16 v179, v228
	ds_write_b16_d16_hi v179, v228 offset:520
	ds_write_b16 v179, v229 offset:1040
	ds_write_b16_d16_hi v179, v229 offset:1560
	ds_write_b16 v179, v230 offset:2080
	ds_write_b16_d16_hi v179, v230 offset:2600
	ds_write_b16 v179, v231 offset:3120
	ds_write_b16_d16_hi v179, v231 offset:3640
	ds_write_b16 v180, v232
	ds_write_b16_d16_hi v180, v232 offset:520
	ds_write_b16 v180, v233 offset:1040
	ds_write_b16_d16_hi v180, v233 offset:1560
	ds_write_b16 v180, v234 offset:2080
	ds_write_b16_d16_hi v180, v234 offset:2600
	ds_write_b16 v180, v235 offset:3120
	ds_write_b16_d16_hi v180, v235 offset:3640
	flat_load_dwordx4 v[208:211], v[2:3] offset:1024
	v_lshl_add_u64 v[0:1], v[144:145], 1, v[0:1]
	flat_load_dwordx4 v[212:215], v[0:1] offset:1024
	v_mov_b32_e32 v4, v72
	v_mov_b32_e32 v5, v72
	s_waitcnt vmcnt(0) lgkmcnt(0)
	ds_write_b16 v181, v208
	ds_write_b16_d16_hi v181, v208 offset:520
	ds_write_b16 v181, v209 offset:1040
	ds_write_b16_d16_hi v181, v209 offset:1560
	ds_write_b16 v181, v210 offset:2080
	ds_write_b16_d16_hi v181, v210 offset:2600
	ds_write_b16 v181, v211 offset:3120
	ds_write_b16_d16_hi v181, v211 offset:3640
	ds_write_b16 v182, v212
	ds_write_b16_d16_hi v182, v212 offset:520
	ds_write_b16 v182, v213 offset:1040
	ds_write_b16_d16_hi v182, v213 offset:1560
	ds_write_b16 v182, v214 offset:2080
	ds_write_b16_d16_hi v182, v214 offset:2600
	ds_write_b16 v182, v215 offset:3120
	ds_write_b16_d16_hi v182, v215 offset:3640
	v_mov_b64_e32 v[0:1], s[84:85]
	v_mad_u64_u32 v[0:1], s[4:5], v154, s74, v[0:1]
	v_mov_b32_e32 v2, v1
	v_mad_u64_u32 v[2:3], s[4:5], v155, s74, v[2:3]
	v_mov_b32_e32 v1, v2
	v_lshl_add_u64 v[0:1], v[0:1], 0, s[26:27]
	v_lshl_add_u64 v[0:1], v[0:1], 0, v[150:151]
	s_mov_b64 s[4:5], 0x1b300f00
	v_lshl_add_u64 v[2:3], v[0:1], 0, s[4:5]
	v_add_co_u32_e32 v0, vcc, 0x1b300000, v0
	s_waitcnt lgkmcnt(0)
	s_nop 0
	v_addc_co_u32_e32 v1, vcc, 0, v1, vcc
	s_barrier
	flat_load_dwordx4 v[98:101], v[0:1] offset:3840
	flat_load_dwordx4 v[102:105], v[2:3] offset:32
	flat_load_dwordx4 v[106:109], v[2:3] offset:64
	flat_load_dwordx4 v[110:113], v[2:3] offset:96
	flat_load_dwordx4 v[114:117], v[2:3] offset:128
	flat_load_dwordx4 v[118:121], v[2:3] offset:160
	flat_load_dwordx4 v[122:125], v[2:3] offset:192
	flat_load_dwordx4 v[126:129], v[2:3] offset:224
	s_mov_b32 s4, 4
	v_mov_b32_e32 v151, v165
	v_mov_b32_e32 v0, 0
	v_mov_b32_e32 v1, v72
	v_mov_b32_e32 v2, v72
	v_mov_b32_e32 v3, v72

; #define LAS __attribute__((address_space(3)))
; __device__ __forceinline__ void mem_unit(Frame& F, const int layer, const int ldp, const int xq_off, const int unit) {
;     ...
; #pragma unroll
;     for (int q = 0; q < 8; ++q) { const int p = F.tid + 512 * q, key = p >> 4, c = p & 15;
;         *(LAS v4u*)(Ks + key * KP + c * 16) = *(const v4u*)(MKV + (size_t)(b * MEMLEN + key) * 4096 + layer * 1024 + head * 128 + 8 * c); }
; #pragma unroll
;     for (int q = 0; q < 8; ++q) { const int p = F.tid + 512 * q, key = p & 255, c = p >> 8;
;         const v4u val = *(const v4u*)(MKV + (size_t)(b * MEMLEN + key) * 4096 + layer * 1024 + 512 + head * 128 + 8 * c);
;         const ldsp vb = Vt + (8 * c) * VP + key * 2;
;         *(LAS bf16*)(vb) = (bf16)(val.x & 0xffff); *(LAS bf16*)(vb + VP) = (bf16)(val.x >> 16); *(LAS bf16*)(vb + 2 * VP) = (bf16)(val.y & 0xffff); *(LAS bf16*)(vb + 3 * VP) = (bf16)(val.y >> 16);
;         *(LAS bf16*)(vb + 4 * VP) = (bf16)(val.z & 0xffff); *(LAS bf16*)(vb + 5 * VP) = (bf16)(val.z >> 16); *(LAS bf16*)(vb + 6 * VP) = (bf16)(val.w & 0xffff); *(LAS bf16*)(vb + 7 * VP) = (bf16)(val.w >> 16); }
;     __syncthreads();
;     const int r = F.lane & 31, h = F.lane >> 5;
;     const size_t row = (size_t)b * SEQ + tb * 256 + 32 * F.wave + r;
;     bf16x8 qf[8];
; #pragma unroll
;     for (int ks = 0; ks < 8; ++ks) qf[ks] = *(const bf16x8*)(P + row * ldp + xq_off + head * 128 + 16 * ks + 8 * h);
;     f32x16 o[4];
; #pragma unroll
;     for (int dt = 0; dt < 4; ++dt)
; #pragma unroll
;         for (int i = 0; i < 16; ++i) o[dt][i] = 0.f;
;     float m = -1e30f, l = 0.f; const NoMask nm;
.LBB0_629:
	s_ashr_i32 s4, s9, 6
	s_lshl_b32 s10, s9, 3
	s_lshl_b32 s5, s4, 8
	s_and_b32 s10, s10, 0x180
	s_lshl_b32 s26, s10, 1
	v_add_u32_e32 v0, s5, v158
	s_add_u32 s14, s0, s26
	v_ashrrev_i32_e32 v1, 31, v0
	s_addc_u32 s15, s1, 0
	v_lshlrev_b64 v[0:1], 13, v[0:1]
	v_lshl_add_u64 v[0:1], s[14:15], 0, v[0:1]
	v_mov_b32_e32 v149, v96
	v_lshl_add_u64 v[0:1], v[0:1], 0, v[148:149]
	flat_load_dwordx4 v[208:211], v[0:1]
	s_lshl_b32 s11, s9, 8
	s_and_b32 s11, s11, 0xf00
	v_mov_b32_e32 v151, v96
	v_mov_b32_e32 v72, 0
	v_mov_b32_e32 v188, 0xf149f2ca
	v_mov_b32_e32 v48, 0
	v_mov_b32_e32 v49, v72
	v_mov_b32_e32 v50, v72
	v_mov_b32_e32 v51, v72
	v_mov_b32_e32 v52, v72
	v_mov_b32_e32 v53, v72
	v_mov_b32_e32 v54, v72
	v_mov_b32_e32 v55, v72
	v_mov_b32_e32 v56, v72
	v_mov_b32_e32 v57, v72
	v_mov_b32_e32 v58, v72
	v_mov_b32_e32 v59, v72
	v_mov_b32_e32 v60, v72
	v_mov_b32_e32 v61, v72
	v_mov_b32_e32 v62, v72
	v_mov_b32_e32 v63, v72
	v_mov_b32_e32 v32, 0
	v_mov_b32_e32 v33, v72
	v_mov_b32_e32 v34, v72
	v_mov_b32_e32 v35, v72
	v_mov_b32_e32 v36, v72
	v_mov_b32_e32 v37, v72
	v_mov_b32_e32 v38, v72
	v_mov_b32_e32 v39, v72
	v_mov_b32_e32 v40, v72
	v_mov_b32_e32 v41, v72
	v_mov_b32_e32 v42, v72
	v_mov_b32_e32 v43, v72
	v_mov_b32_e32 v44, v72
	v_mov_b32_e32 v45, v72
	v_mov_b32_e32 v46, v72
	v_mov_b32_e32 v47, v72
	v_mov_b32_e32 v16, 0
	v_mov_b32_e32 v17, v72
	v_mov_b32_e32 v18, v72
	v_mov_b32_e32 v19, v72
	v_mov_b32_e32 v20, v72
	v_mov_b32_e32 v21, v72
	v_mov_b32_e32 v22, v72
	v_mov_b32_e32 v23, v72
	v_mov_b32_e32 v24, v72
	v_mov_b32_e32 v25, v72
	v_mov_b32_e32 v26, v72
	v_mov_b32_e32 v27, v72
	v_mov_b32_e32 v28, v72
	v_mov_b32_e32 v29, v72
	v_mov_b32_e32 v30, v72
	v_mov_b32_e32 v31, v72
	v_mov_b32_e32 v6, v72
	v_mov_b32_e32 v7, v72
	v_mov_b32_e32 v8, v72
	v_mov_b32_e32 v9, v72
	v_mov_b32_e32 v10, v72
	v_mov_b32_e32 v11, v72
	v_mov_b32_e32 v12, v72
	v_mov_b32_e32 v13, v72
	v_mov_b32_e32 v14, v72
	v_mov_b32_e32 v15, v72
	v_add_u32_e32 v0, s5, v159
	v_ashrrev_i32_e32 v1, 31, v0
	v_lshlrev_b64 v[0:1], 13, v[0:1]
	v_lshl_add_u64 v[0:1], s[14:15], 0, v[0:1]
	v_lshl_add_u64 v[0:1], v[0:1], 0, v[148:149]
	flat_load_dwordx4 v[212:215], v[0:1]
	v_add_u32_e32 v0, s5, v160
	v_ashrrev_i32_e32 v1, 31, v0
	v_lshlrev_b64 v[0:1], 13, v[0:1]
	v_lshl_add_u64 v[0:1], s[14:15], 0, v[0:1]
	v_lshl_add_u64 v[0:1], v[0:1], 0, v[148:149]
	flat_load_dwordx4 v[216:219], v[0:1]
	v_add_u32_e32 v0, s5, v161
	v_ashrrev_i32_e32 v1, 31, v0
	v_lshlrev_b64 v[0:1], 13, v[0:1]
	v_lshl_add_u64 v[0:1], s[14:15], 0, v[0:1]
	v_lshl_add_u64 v[0:1], v[0:1], 0, v[148:149]
	flat_load_dwordx4 v[220:223], v[0:1]
	v_add_u32_e32 v0, s5, v164
	v_ashrrev_i32_e32 v1, 31, v0
	v_lshlrev_b64 v[0:1], 13, v[0:1]
	v_lshl_add_u64 v[0:1], s[14:15], 0, v[0:1]
	v_lshl_add_u64 v[0:1], v[0:1], 0, v[148:149]
	flat_load_dwordx4 v[224:227], v[0:1]
	v_add_u32_e32 v0, s5, v165
	v_ashrrev_i32_e32 v1, 31, v0
	v_lshlrev_b64 v[0:1], 13, v[0:1]
	v_lshl_add_u64 v[0:1], s[14:15], 0, v[0:1]
	v_lshl_add_u64 v[0:1], v[0:1], 0, v[148:149]
	flat_load_dwordx4 v[228:231], v[0:1]
	v_add_u32_e32 v0, s5, v166
	v_ashrrev_i32_e32 v1, 31, v0
	v_lshlrev_b64 v[0:1], 13, v[0:1]
	v_lshl_add_u64 v[0:1], s[14:15], 0, v[0:1]
	v_lshl_add_u64 v[0:1], v[0:1], 0, v[148:149]
	flat_load_dwordx4 v[232:235], v[0:1]
	v_add_u32_e32 v0, s5, v167
	v_ashrrev_i32_e32 v1, 31, v0
	v_lshlrev_b64 v[0:1], 13, v[0:1]
	v_lshl_add_u64 v[0:1], s[14:15], 0, v[0:1]
	v_lshl_add_u64 v[0:1], v[0:1], 0, v[148:149]
	s_waitcnt vmcnt(0) lgkmcnt(0)
	ds_write_b128 v172, v[208:211]
	ds_write_b128 v173, v[212:215]
	ds_write_b128 v174, v[216:219]
	ds_write_b128 v175, v[220:223]
	ds_write_b128 v176, v[224:227]
	ds_write_b128 v177, v[228:231]
	ds_write_b128 v178, v[232:235]
	flat_load_dwordx4 v[208:211], v[0:1]
	v_mov_b32_e32 v149, v171
	v_or_b32_e32 v0, s5, v168
	v_ashrrev_i32_e32 v1, 31, v0
	v_lshlrev_b64 v[0:1], 13, v[0:1]
	v_lshl_add_u64 v[0:1], s[0:1], 0, v[0:1]
	v_lshl_add_u64 v[0:1], v[0:1], 0, s[26:27]
	v_lshl_add_u64 v[2:3], v[130:131], 1, v[0:1]
	flat_load_dwordx4 v[212:215], v[2:3] offset:1024
	s_ashr_i32 s5, s4, 31
	s_lshl_b64 s[4:5], s[4:5], 12
	s_or_b32 s4, s4, s11
	v_lshl_add_u64 v[154:155], s[4:5], 0, v[146:147]
	v_lshl_add_u64 v[2:3], v[132:133], 1, v[0:1]
	flat_load_dwordx4 v[216:219], v[2:3] offset:1024
	v_lshl_add_u64 v[2:3], v[134:135], 1, v[0:1]
	flat_load_dwordx4 v[220:223], v[2:3] offset:1024
	v_lshl_add_u64 v[2:3], v[136:137], 1, v[0:1]
	flat_load_dwordx4 v[224:227], v[2:3] offset:1024
	v_lshl_add_u64 v[2:3], v[138:139], 1, v[0:1]
	flat_load_dwordx4 v[228:231], v[2:3] offset:1024
	v_lshl_add_u64 v[2:3], v[140:141], 1, v[0:1]
	flat_load_dwordx4 v[232:235], v[2:3] offset:1024
	v_lshl_add_u64 v[2:3], v[142:143], 1, v[0:1]
	s_waitcnt vmcnt(0) lgkmcnt(0)
; #define LAS __attribute__((address_space(3)))
; __device__ __forceinline__ void mem_unit(Frame& F, const int layer, const int ldp, const int xq_off, const int unit) {
;     ...
;     for (int q = 0; q < 8; ++q) { const int p = F.tid + 512 * q, key = p & 255, c = p >> 8;
;         const v4u val = *(const v4u*)(MKV + (size_t)(b * MEMLEN + key) * 4096 + layer * 1024 + 512 + head * 128 + 8 * c);
;         const ldsp vb = Vt + (8 * c) * VP + key * 2;
;         *(LAS bf16*)(vb) = (bf16)(val.x & 0xffff); *(LAS bf16*)(vb + VP) = (bf16)(val.x >> 16); *(LAS bf16*)(vb + 2 * VP) = (bf16)(val.y & 0xffff); *(LAS bf16*)(vb + 3 * VP) = (bf16)(val.y >> 16);
;         *(LAS bf16*)(vb + 4 * VP) = (bf16)(val.z & 0xffff); *(LAS bf16*)(vb + 5 * VP) = (bf16)(val.z >> 16); *(LAS bf16*)(vb + 6 * VP) = (bf16)(val.w & 0xffff); *(LAS bf16*)(vb + 7 * VP) = (bf16)(val.w >> 16); }
;     __syncthreads();
;     const int r = F.lane & 31, h = F.lane >> 5;
;     const size_t row = (size_t)b * SEQ + tb * 256 + 32 * F.wave + r;
;     bf16x8 qf[8];
; #pragma unroll
;     for (int ks = 0; ks < 8; ++ks) qf[ks] = *(const bf16x8*)(P + row * ldp + xq_off + head * 128 + 16 * ks + 8 * h);
	ds_write_b128 v179, v[208:211]
	ds_write_b16 v180, v212
	ds_write_b16_d16_hi v180, v212 offset:520
	ds_write_b16 v180, v213 offset:1040
	ds_write_b16_d16_hi v180, v213 offset:1560
	ds_write_b16 v180, v214 offset:2080
	ds_write_b16_d16_hi v180, v214 offset:2600
	ds_write_b16 v180, v215 offset:3120
	ds_write_b16_d16_hi v180, v215 offset:3640
	ds_write_b16 v181, v216
	ds_write_b16_d16_hi v181, v216 offset:520
	ds_write_b16 v181, v217 offset:1040
	ds_write_b16_d16_hi v181, v217 offset:1560
	ds_write_b16 v181, v218 offset:2080
	ds_write_b16_d16_hi v181, v218 offset:2600
	ds_write_b16 v181, v219 offset:3120
	ds_write_b16_d16_hi v181, v219 offset:3640
	ds_write_b16 v182, v220
	ds_write_b16_d16_hi v182, v220 offset:520
	ds_write_b16 v182, v221 offset:1040
	ds_write_b16_d16_hi v182, v221 offset:1560
	ds_write_b16 v182, v222 offset:2080
	ds_write_b16_d16_hi v182, v222 offset:2600
	ds_write_b16 v182, v223 offset:3120
	ds_write_b16_d16_hi v182, v223 offset:3640
	ds_write_b16 v183, v224
	ds_write_b16_d16_hi v183, v224 offset:520
	ds_write_b16 v183, v225 offset:1040
	ds_write_b16_d16_hi v183, v225 offset:1560
	ds_write_b16 v183, v226 offset:2080
	ds_write_b16_d16_hi v183, v226 offset:2600
	ds_write_b16 v183, v227 offset:3120
	ds_write_b16_d16_hi v183, v227 offset:3640
	ds_write_b16 v184, v228
	ds_write_b16_d16_hi v184, v228 offset:520
	ds_write_b16 v184, v229 offset:1040
	ds_write_b16_d16_hi v184, v229 offset:1560
	ds_write_b16 v184, v230 offset:2080
	ds_write_b16_d16_hi v184, v230 offset:2600
	ds_write_b16 v184, v231 offset:3120
	ds_write_b16_d16_hi v184, v231 offset:3640
	ds_write_b16 v185, v232
	ds_write_b16_d16_hi v185, v232 offset:520
	ds_write_b16 v185, v233 offset:1040
	ds_write_b16_d16_hi v185, v233 offset:1560
	ds_write_b16 v185, v234 offset:2080
	ds_write_b16_d16_hi v185, v234 offset:2600
	ds_write_b16 v185, v235 offset:3120
	ds_write_b16_d16_hi v185, v235 offset:3640
	flat_load_dwordx4 v[208:211], v[2:3] offset:1024
	v_lshl_add_u64 v[0:1], v[144:145], 1, v[0:1]
	flat_load_dwordx4 v[212:215], v[0:1] offset:1024
	v_mov_b32_e32 v4, v72
	v_mov_b32_e32 v5, v72
	s_waitcnt vmcnt(0) lgkmcnt(0)
	ds_write_b16 v186, v208
	ds_write_b16_d16_hi v186, v208 offset:520
	ds_write_b16 v186, v209 offset:1040
	ds_write_b16_d16_hi v186, v209 offset:1560
	ds_write_b16 v186, v210 offset:2080
	ds_write_b16_d16_hi v186, v210 offset:2600
	ds_write_b16 v186, v211 offset:3120
	ds_write_b16_d16_hi v186, v211 offset:3640
	ds_write_b16 v187, v212
	ds_write_b16_d16_hi v187, v212 offset:520
	ds_write_b16 v187, v213 offset:1040
	ds_write_b16_d16_hi v187, v213 offset:1560
	ds_write_b16 v187, v214 offset:2080
	ds_write_b16_d16_hi v187, v214 offset:2600
	ds_write_b16 v187, v215 offset:3120
	ds_write_b16_d16_hi v187, v215 offset:3640
	v_mov_b64_e32 v[0:1], s[42:43]
	v_mad_u64_u32 v[0:1], s[4:5], v154, s91, v[0:1]
	v_mov_b32_e32 v2, v1
	v_mad_u64_u32 v[2:3], s[4:5], v155, s91, v[2:3]
	v_mov_b32_e32 v1, v2
	v_lshl_add_u64 v[0:1], v[0:1], 0, s[26:27]
	v_lshl_add_u64 v[0:1], v[0:1], 0, v[150:151]
	s_mov_b64 s[4:5], 0x1b302820
	v_lshl_add_u64 v[2:3], v[0:1], 0, s[4:5]
	v_add_co_u32_e32 v0, vcc, 0x1b302000, v0
	s_waitcnt lgkmcnt(0)
	s_nop 0
	v_addc_co_u32_e32 v1, vcc, 0, v1, vcc
	s_barrier
	flat_load_dwordx4 v[98:101], v[0:1] offset:2080
	flat_load_dwordx4 v[102:105], v[2:3] offset:32
	flat_load_dwordx4 v[106:109], v[2:3] offset:64
	flat_load_dwordx4 v[110:113], v[2:3] offset:96
	flat_load_dwordx4 v[114:117], v[2:3] offset:128
	flat_load_dwordx4 v[118:121], v[2:3] offset:160
	flat_load_dwordx4 v[122:125], v[2:3] offset:192
	flat_load_dwordx4 v[126:129], v[2:3] offset:224
	s_mov_b32 s4, 4
	v_mov_b32_e32 v151, v170
	v_mov_b32_e32 v0, 0
	v_mov_b32_e32 v1, v72
	v_mov_b32_e32 v2, v72
	v_mov_b32_e32 v3, v72
